# phase 15 transpose loop: steady-state entry with counted waits vmcnt(7,6,5,4) so the prefetched rows do not wait for the previous tile's stores
# speedup vs baseline: 1.0021x; 1.0021x over previous
.Lp15_steady:
	s_lshl_b32 s0, s4, 15
	s_add_i32 s12, s0, 0
	v_readlane_b32 s16, v249, 12
	v_add3_u32 v34, s12, v22, v30
	v_readlane_b32 s22, v249, 18
	s_waitcnt vmcnt(7)
	ds_write_b128 v34, v[0:3]
	v_add3_u32 v34, s12, v23, v31
	s_add_i32 s6, s6, s22
	s_waitcnt vmcnt(6)
	ds_write_b128 v34, v[4:7]
	v_add3_u32 v34, s12, v24, v32
	s_cmpk_gt_i32 s6, 0x7ff
	s_waitcnt vmcnt(5)
	ds_write_b128 v34, v[8:11]
	v_add3_u32 v34, s12, v25, v33
	s_cselect_b64 s[0:1], -1, 0
	s_cmpk_lt_i32 s6, 0x800
	s_mov_b64 s[2:3], -1
	v_readlane_b32 s13, v253, 63
	s_waitcnt vmcnt(4)
	ds_write_b128 v34, v[12:15]
	s_branch .Lp15_cont

.Lp15_cont:
	v_readlane_b32 s17, v249, 13
	v_readlane_b32 s18, v249, 14
	v_readlane_b32 s19, v249, 15
	v_readlane_b32 s20, v249, 16
	v_readlane_b32 s21, v249, 17
	v_readlane_b32 s23, v249, 19
	s_cbranch_scc1 .LBB0_192
	v_readlane_b32 s2, v254, 0
	s_add_i32 s9, s7, s13
	s_add_i32 s10, s8, s2
	s_mov_b64 s[2:3], 0
